# P2 conv4 sliding-window path with throttled loads (16 rows ahead, reads and writes interleaved)
# baseline (speedup 1.0000x reference)
.LBB0_669:
	s_or_b64 exec, exec, s[38:39]
	s_cmp_eq_u32 s92, 0x100
	s_cbranch_scc0 .Lp2b_compiled
	v_mbcnt_lo_u32_b32 v0, -1, 0
	v_mbcnt_hi_u32_b32 v0, -1, v0
	s_lshl_b32 s4, s2, 3
	s_add_i32 s4, s4, s33
	s_lshl_b32 s4, s4, 5
	v_lshlrev_b32_e32 v1, 4, v0
	v_lshlrev_b32_e32 v2, 5, v0
	v_add_u32_e32 v3, 0x1000, v2
	s_lshl_b32 s5, s4, 10
	s_mov_b32 s6, 0
	s_add_u32 s8, s96, 0x1d800000
	s_addc_u32 s9, s97, 0
	s_add_u32 s8, s8, s5
	s_addc_u32 s9, s9, 0
	s_add_u32 s10, s96, 0x27800000
	s_addc_u32 s11, s97, 0
	s_add_u32 s10, s10, s5
	s_addc_u32 s11, s11, 0
	s_and_b32 s12, s4, 0x7ff
	s_cmp_eq_u32 s12, 0
	s_cselect_b32 s12, 0, 0xc00
	s_sub_u32 s14, s8, s12
	s_subb_u32 s15, s9, 0
	global_load_dwordx4 v[8:11], v2, s[70:71]
	global_load_dwordx4 v[12:15], v2, s[70:71] offset:16
	global_load_dwordx4 v[16:19], v2, s[70:71] offset:2048
	global_load_dwordx4 v[20:23], v2, s[70:71] offset:2064
	global_load_dwordx4 v[24:27], v3, s[70:71]
	global_load_dwordx4 v[28:31], v3, s[70:71] offset:16
	global_load_dwordx4 v[32:35], v3, s[70:71] offset:2048
	global_load_dwordx4 v[36:39], v3, s[70:71] offset:2064
	global_load_dwordx4 v[72:75], v2, s[72:73]
	global_load_dwordx4 v[76:79], v2, s[72:73] offset:16
	global_load_dwordx4 v[100:103], v1, s[14:15]
	global_load_dwordx4 v[104:107], v1, s[14:15] offset:1024
	global_load_dwordx4 v[108:111], v1, s[14:15] offset:2048
	global_load_dwordx4 v[112:115], v1, s[8:9]
	global_load_dwordx4 v[116:119], v1, s[8:9] offset:1024
	global_load_dwordx4 v[120:123], v1, s[8:9] offset:2048
	global_load_dwordx4 v[124:127], v1, s[8:9] offset:3072
	s_add_u32 s8, s8, 0x1000
	s_addc_u32 s9, s9, 0
	global_load_dwordx4 v[128:131], v1, s[8:9]
	global_load_dwordx4 v[132:135], v1, s[8:9] offset:1024
	global_load_dwordx4 v[136:139], v1, s[8:9] offset:2048
	global_load_dwordx4 v[140:143], v1, s[8:9] offset:3072
	s_add_u32 s8, s8, 0x1000
	s_addc_u32 s9, s9, 0
	global_load_dwordx4 v[144:147], v1, s[8:9]
	global_load_dwordx4 v[148:151], v1, s[8:9] offset:1024
	global_load_dwordx4 v[152:155], v1, s[8:9] offset:2048
	global_load_dwordx4 v[156:159], v1, s[8:9] offset:3072
	s_add_u32 s8, s8, 0x1000
	s_addc_u32 s9, s9, 0
	global_load_dwordx4 v[160:163], v1, s[8:9]
	global_load_dwordx4 v[164:167], v1, s[8:9] offset:1024
	global_load_dwordx4 v[168:171], v1, s[8:9] offset:2048
	global_load_dwordx4 v[172:175], v1, s[8:9] offset:3072
	s_add_u32 s8, s8, 0x1000
	s_addc_u32 s9, s9, 0
	s_waitcnt vmcnt(16)
	v_lshlrev_b32_e32 v48, 16, v100
	v_and_b32_e32 v49, 0xffff0000, v100
	v_lshlrev_b32_e32 v50, 16, v101
	v_and_b32_e32 v51, 0xffff0000, v101
	v_lshlrev_b32_e32 v52, 16, v102
	v_and_b32_e32 v53, 0xffff0000, v102
	v_lshlrev_b32_e32 v54, 16, v103
	v_and_b32_e32 v55, 0xffff0000, v103
	v_lshlrev_b32_e32 v56, 16, v104
	v_and_b32_e32 v57, 0xffff0000, v104
	v_lshlrev_b32_e32 v58, 16, v105
	v_and_b32_e32 v59, 0xffff0000, v105
	v_lshlrev_b32_e32 v60, 16, v106
	v_and_b32_e32 v61, 0xffff0000, v106
	v_lshlrev_b32_e32 v62, 16, v107
	v_and_b32_e32 v63, 0xffff0000, v107
	v_lshlrev_b32_e32 v64, 16, v108
	v_and_b32_e32 v65, 0xffff0000, v108
	v_lshlrev_b32_e32 v66, 16, v109
	v_and_b32_e32 v67, 0xffff0000, v109
	v_lshlrev_b32_e32 v68, 16, v110
	v_and_b32_e32 v69, 0xffff0000, v110
	v_lshlrev_b32_e32 v70, 16, v111
	v_and_b32_e32 v71, 0xffff0000, v111
	s_cmp_eq_u32 s12, 0
	s_cbranch_scc0 .Lp2b_halo
	v_mov_b64_e32 v[48:49], 0
	v_mov_b64_e32 v[50:51], 0
	v_mov_b64_e32 v[52:53], 0
	v_mov_b64_e32 v[54:55], 0
	v_mov_b64_e32 v[56:57], 0
	v_mov_b64_e32 v[58:59], 0
	v_mov_b64_e32 v[60:61], 0
	v_mov_b64_e32 v[62:63], 0
	v_mov_b64_e32 v[64:65], 0
	v_mov_b64_e32 v[66:67], 0
	v_mov_b64_e32 v[68:69], 0
	v_mov_b64_e32 v[70:71], 0
.Lp2b_halo:
	s_waitcnt vmcnt(15)
	v_lshlrev_b32_e32 v40, 16, v112
	v_and_b32_e32 v41, 0xffff0000, v112
	v_lshlrev_b32_e32 v42, 16, v113
	v_and_b32_e32 v43, 0xffff0000, v113
	v_lshlrev_b32_e32 v44, 16, v114
	v_and_b32_e32 v45, 0xffff0000, v114
	v_lshlrev_b32_e32 v46, 16, v115
	v_and_b32_e32 v47, 0xffff0000, v115
	v_pk_fma_f32 v[80:81], v[48:49], v[8:9], v[72:73]
	v_pk_fma_f32 v[82:83], v[50:51], v[10:11], v[74:75]
	v_pk_fma_f32 v[84:85], v[52:53], v[12:13], v[76:77]
	v_pk_fma_f32 v[86:87], v[54:55], v[14:15], v[78:79]
	v_pk_fma_f32 v[80:81], v[56:57], v[16:17], v[80:81]
	v_pk_fma_f32 v[82:83], v[58:59], v[18:19], v[82:83]
	v_pk_fma_f32 v[84:85], v[60:61], v[20:21], v[84:85]
	v_pk_fma_f32 v[86:87], v[62:63], v[22:23], v[86:87]
	v_pk_fma_f32 v[80:81], v[64:65], v[24:25], v[80:81]
	v_pk_fma_f32 v[82:83], v[66:67], v[26:27], v[82:83]
	v_pk_fma_f32 v[84:85], v[68:69], v[28:29], v[84:85]
	v_pk_fma_f32 v[86:87], v[70:71], v[30:31], v[86:87]
	v_pk_fma_f32 v[80:81], v[40:41], v[32:33], v[80:81]
	v_pk_fma_f32 v[82:83], v[42:43], v[34:35], v[82:83]
	v_pk_fma_f32 v[84:85], v[44:45], v[36:37], v[84:85]
	v_pk_fma_f32 v[86:87], v[46:47], v[38:39], v[86:87]
	v_cvt_pk_bf16_f32 v88, v80, v81
	v_cvt_pk_bf16_f32 v89, v82, v83
	v_cvt_pk_bf16_f32 v90, v84, v85
	v_cvt_pk_bf16_f32 v91, v86, v87
	global_store_dwordx4 v1, v[88:91], s[10:11]
	global_load_dwordx4 v[176:179], v1, s[8:9]
	s_waitcnt vmcnt(16)
	v_lshlrev_b32_e32 v48, 16, v116
	v_and_b32_e32 v49, 0xffff0000, v116
	v_lshlrev_b32_e32 v50, 16, v117
	v_and_b32_e32 v51, 0xffff0000, v117
	v_lshlrev_b32_e32 v52, 16, v118
	v_and_b32_e32 v53, 0xffff0000, v118
	v_lshlrev_b32_e32 v54, 16, v119
	v_and_b32_e32 v55, 0xffff0000, v119
	v_pk_fma_f32 v[80:81], v[56:57], v[8:9], v[72:73]
	v_pk_fma_f32 v[82:83], v[58:59], v[10:11], v[74:75]
	v_pk_fma_f32 v[84:85], v[60:61], v[12:13], v[76:77]
	v_pk_fma_f32 v[86:87], v[62:63], v[14:15], v[78:79]
	v_pk_fma_f32 v[80:81], v[64:65], v[16:17], v[80:81]
	v_pk_fma_f32 v[82:83], v[66:67], v[18:19], v[82:83]
	v_pk_fma_f32 v[84:85], v[68:69], v[20:21], v[84:85]
	v_pk_fma_f32 v[86:87], v[70:71], v[22:23], v[86:87]
	v_pk_fma_f32 v[80:81], v[40:41], v[24:25], v[80:81]
	v_pk_fma_f32 v[82:83], v[42:43], v[26:27], v[82:83]
	v_pk_fma_f32 v[84:85], v[44:45], v[28:29], v[84:85]
	v_pk_fma_f32 v[86:87], v[46:47], v[30:31], v[86:87]
	v_pk_fma_f32 v[80:81], v[48:49], v[32:33], v[80:81]
	v_pk_fma_f32 v[82:83], v[50:51], v[34:35], v[82:83]
	v_pk_fma_f32 v[84:85], v[52:53], v[36:37], v[84:85]
	v_pk_fma_f32 v[86:87], v[54:55], v[38:39], v[86:87]
	v_cvt_pk_bf16_f32 v88, v80, v81
	v_cvt_pk_bf16_f32 v89, v82, v83
	v_cvt_pk_bf16_f32 v90, v84, v85
	v_cvt_pk_bf16_f32 v91, v86, v87
	global_store_dwordx4 v1, v[88:91], s[10:11] offset:1024
	global_load_dwordx4 v[180:183], v1, s[8:9] offset:1024
	s_waitcnt vmcnt(17)
	v_lshlrev_b32_e32 v56, 16, v120
	v_and_b32_e32 v57, 0xffff0000, v120
	v_lshlrev_b32_e32 v58, 16, v121
	v_and_b32_e32 v59, 0xffff0000, v121
	v_lshlrev_b32_e32 v60, 16, v122
	v_and_b32_e32 v61, 0xffff0000, v122
	v_lshlrev_b32_e32 v62, 16, v123
	v_and_b32_e32 v63, 0xffff0000, v123
	v_pk_fma_f32 v[80:81], v[64:65], v[8:9], v[72:73]
	v_pk_fma_f32 v[82:83], v[66:67], v[10:11], v[74:75]
	v_pk_fma_f32 v[84:85], v[68:69], v[12:13], v[76:77]
	v_pk_fma_f32 v[86:87], v[70:71], v[14:15], v[78:79]
	v_pk_fma_f32 v[80:81], v[40:41], v[16:17], v[80:81]
	v_pk_fma_f32 v[82:83], v[42:43], v[18:19], v[82:83]
	v_pk_fma_f32 v[84:85], v[44:45], v[20:21], v[84:85]
	v_pk_fma_f32 v[86:87], v[46:47], v[22:23], v[86:87]
	v_pk_fma_f32 v[80:81], v[48:49], v[24:25], v[80:81]
	v_pk_fma_f32 v[82:83], v[50:51], v[26:27], v[82:83]
	v_pk_fma_f32 v[84:85], v[52:53], v[28:29], v[84:85]
	v_pk_fma_f32 v[86:87], v[54:55], v[30:31], v[86:87]
	v_pk_fma_f32 v[80:81], v[56:57], v[32:33], v[80:81]
	v_pk_fma_f32 v[82:83], v[58:59], v[34:35], v[82:83]
	v_pk_fma_f32 v[84:85], v[60:61], v[36:37], v[84:85]
	v_pk_fma_f32 v[86:87], v[62:63], v[38:39], v[86:87]
	v_cvt_pk_bf16_f32 v88, v80, v81
	v_cvt_pk_bf16_f32 v89, v82, v83
	v_cvt_pk_bf16_f32 v90, v84, v85
	v_cvt_pk_bf16_f32 v91, v86, v87
	global_store_dwordx4 v1, v[88:91], s[10:11] offset:2048
	global_load_dwordx4 v[184:187], v1, s[8:9] offset:2048
	s_waitcnt vmcnt(18)
	v_lshlrev_b32_e32 v64, 16, v124
	v_and_b32_e32 v65, 0xffff0000, v124
	v_lshlrev_b32_e32 v66, 16, v125
	v_and_b32_e32 v67, 0xffff0000, v125
	v_lshlrev_b32_e32 v68, 16, v126
	v_and_b32_e32 v69, 0xffff0000, v126
	v_lshlrev_b32_e32 v70, 16, v127
	v_and_b32_e32 v71, 0xffff0000, v127
	v_pk_fma_f32 v[80:81], v[40:41], v[8:9], v[72:73]
	v_pk_fma_f32 v[82:83], v[42:43], v[10:11], v[74:75]
	v_pk_fma_f32 v[84:85], v[44:45], v[12:13], v[76:77]
	v_pk_fma_f32 v[86:87], v[46:47], v[14:15], v[78:79]
	v_pk_fma_f32 v[80:81], v[48:49], v[16:17], v[80:81]
	v_pk_fma_f32 v[82:83], v[50:51], v[18:19], v[82:83]
	v_pk_fma_f32 v[84:85], v[52:53], v[20:21], v[84:85]
	v_pk_fma_f32 v[86:87], v[54:55], v[22:23], v[86:87]
	v_pk_fma_f32 v[80:81], v[56:57], v[24:25], v[80:81]
	v_pk_fma_f32 v[82:83], v[58:59], v[26:27], v[82:83]
	v_pk_fma_f32 v[84:85], v[60:61], v[28:29], v[84:85]
	v_pk_fma_f32 v[86:87], v[62:63], v[30:31], v[86:87]
	v_pk_fma_f32 v[80:81], v[64:65], v[32:33], v[80:81]
	v_pk_fma_f32 v[82:83], v[66:67], v[34:35], v[82:83]
	v_pk_fma_f32 v[84:85], v[68:69], v[36:37], v[84:85]
	v_pk_fma_f32 v[86:87], v[70:71], v[38:39], v[86:87]
	v_cvt_pk_bf16_f32 v88, v80, v81
	v_cvt_pk_bf16_f32 v89, v82, v83
	v_cvt_pk_bf16_f32 v90, v84, v85
	v_cvt_pk_bf16_f32 v91, v86, v87
	global_store_dwordx4 v1, v[88:91], s[10:11] offset:3072
	global_load_dwordx4 v[188:191], v1, s[8:9] offset:3072
	s_add_u32 s8, s8, 0x1000
	s_addc_u32 s9, s9, 0
	s_waitcnt vmcnt(19)
	v_lshlrev_b32_e32 v40, 16, v128
	v_and_b32_e32 v41, 0xffff0000, v128
	v_lshlrev_b32_e32 v42, 16, v129
	v_and_b32_e32 v43, 0xffff0000, v129
	v_lshlrev_b32_e32 v44, 16, v130
	v_and_b32_e32 v45, 0xffff0000, v130
	v_lshlrev_b32_e32 v46, 16, v131
	v_and_b32_e32 v47, 0xffff0000, v131
	v_pk_fma_f32 v[80:81], v[48:49], v[8:9], v[72:73]
	v_pk_fma_f32 v[82:83], v[50:51], v[10:11], v[74:75]
	v_pk_fma_f32 v[84:85], v[52:53], v[12:13], v[76:77]
	v_pk_fma_f32 v[86:87], v[54:55], v[14:15], v[78:79]
	v_pk_fma_f32 v[80:81], v[56:57], v[16:17], v[80:81]
	v_pk_fma_f32 v[82:83], v[58:59], v[18:19], v[82:83]
	v_pk_fma_f32 v[84:85], v[60:61], v[20:21], v[84:85]
	v_pk_fma_f32 v[86:87], v[62:63], v[22:23], v[86:87]
	v_pk_fma_f32 v[80:81], v[64:65], v[24:25], v[80:81]
	v_pk_fma_f32 v[82:83], v[66:67], v[26:27], v[82:83]
	v_pk_fma_f32 v[84:85], v[68:69], v[28:29], v[84:85]
	v_pk_fma_f32 v[86:87], v[70:71], v[30:31], v[86:87]
	v_pk_fma_f32 v[80:81], v[40:41], v[32:33], v[80:81]
	v_pk_fma_f32 v[82:83], v[42:43], v[34:35], v[82:83]
	v_pk_fma_f32 v[84:85], v[44:45], v[36:37], v[84:85]
	v_pk_fma_f32 v[86:87], v[46:47], v[38:39], v[86:87]
	v_cvt_pk_bf16_f32 v88, v80, v81
	v_cvt_pk_bf16_f32 v89, v82, v83
	v_cvt_pk_bf16_f32 v90, v84, v85
	v_cvt_pk_bf16_f32 v91, v86, v87
	s_add_u32 s10, s10, 0x1000
	s_addc_u32 s11, s11, 0
	global_store_dwordx4 v1, v[88:91], s[10:11]
	global_load_dwordx4 v[192:195], v1, s[8:9]
	s_waitcnt vmcnt(20)
	v_lshlrev_b32_e32 v48, 16, v132
	v_and_b32_e32 v49, 0xffff0000, v132
	v_lshlrev_b32_e32 v50, 16, v133
	v_and_b32_e32 v51, 0xffff0000, v133
	v_lshlrev_b32_e32 v52, 16, v134
	v_and_b32_e32 v53, 0xffff0000, v134
	v_lshlrev_b32_e32 v54, 16, v135
	v_and_b32_e32 v55, 0xffff0000, v135
	v_pk_fma_f32 v[80:81], v[56:57], v[8:9], v[72:73]
	v_pk_fma_f32 v[82:83], v[58:59], v[10:11], v[74:75]
	v_pk_fma_f32 v[84:85], v[60:61], v[12:13], v[76:77]
	v_pk_fma_f32 v[86:87], v[62:63], v[14:15], v[78:79]
	v_pk_fma_f32 v[80:81], v[64:65], v[16:17], v[80:81]
	v_pk_fma_f32 v[82:83], v[66:67], v[18:19], v[82:83]
	v_pk_fma_f32 v[84:85], v[68:69], v[20:21], v[84:85]
	v_pk_fma_f32 v[86:87], v[70:71], v[22:23], v[86:87]
	v_pk_fma_f32 v[80:81], v[40:41], v[24:25], v[80:81]
	v_pk_fma_f32 v[82:83], v[42:43], v[26:27], v[82:83]
	v_pk_fma_f32 v[84:85], v[44:45], v[28:29], v[84:85]
	v_pk_fma_f32 v[86:87], v[46:47], v[30:31], v[86:87]
	v_pk_fma_f32 v[80:81], v[48:49], v[32:33], v[80:81]
	v_pk_fma_f32 v[82:83], v[50:51], v[34:35], v[82:83]
	v_pk_fma_f32 v[84:85], v[52:53], v[36:37], v[84:85]
	v_pk_fma_f32 v[86:87], v[54:55], v[38:39], v[86:87]
	v_cvt_pk_bf16_f32 v88, v80, v81
	v_cvt_pk_bf16_f32 v89, v82, v83
	v_cvt_pk_bf16_f32 v90, v84, v85
	v_cvt_pk_bf16_f32 v91, v86, v87
	global_store_dwordx4 v1, v[88:91], s[10:11] offset:1024
	global_load_dwordx4 v[196:199], v1, s[8:9] offset:1024
	s_waitcnt vmcnt(21)
	v_lshlrev_b32_e32 v56, 16, v136
	v_and_b32_e32 v57, 0xffff0000, v136
	v_lshlrev_b32_e32 v58, 16, v137
	v_and_b32_e32 v59, 0xffff0000, v137
	v_lshlrev_b32_e32 v60, 16, v138
	v_and_b32_e32 v61, 0xffff0000, v138
	v_lshlrev_b32_e32 v62, 16, v139
	v_and_b32_e32 v63, 0xffff0000, v139
	v_pk_fma_f32 v[80:81], v[64:65], v[8:9], v[72:73]
	v_pk_fma_f32 v[82:83], v[66:67], v[10:11], v[74:75]
	v_pk_fma_f32 v[84:85], v[68:69], v[12:13], v[76:77]
	v_pk_fma_f32 v[86:87], v[70:71], v[14:15], v[78:79]
	v_pk_fma_f32 v[80:81], v[40:41], v[16:17], v[80:81]
	v_pk_fma_f32 v[82:83], v[42:43], v[18:19], v[82:83]
	v_pk_fma_f32 v[84:85], v[44:45], v[20:21], v[84:85]
	v_pk_fma_f32 v[86:87], v[46:47], v[22:23], v[86:87]
	v_pk_fma_f32 v[80:81], v[48:49], v[24:25], v[80:81]
	v_pk_fma_f32 v[82:83], v[50:51], v[26:27], v[82:83]
	v_pk_fma_f32 v[84:85], v[52:53], v[28:29], v[84:85]
	v_pk_fma_f32 v[86:87], v[54:55], v[30:31], v[86:87]
	v_pk_fma_f32 v[80:81], v[56:57], v[32:33], v[80:81]
	v_pk_fma_f32 v[82:83], v[58:59], v[34:35], v[82:83]
	v_pk_fma_f32 v[84:85], v[60:61], v[36:37], v[84:85]
	v_pk_fma_f32 v[86:87], v[62:63], v[38:39], v[86:87]
	v_cvt_pk_bf16_f32 v88, v80, v81
	v_cvt_pk_bf16_f32 v89, v82, v83
	v_cvt_pk_bf16_f32 v90, v84, v85
	v_cvt_pk_bf16_f32 v91, v86, v87
	global_store_dwordx4 v1, v[88:91], s[10:11] offset:2048
	global_load_dwordx4 v[200:203], v1, s[8:9] offset:2048
	s_waitcnt vmcnt(22)
	v_lshlrev_b32_e32 v64, 16, v140
	v_and_b32_e32 v65, 0xffff0000, v140
	v_lshlrev_b32_e32 v66, 16, v141
	v_and_b32_e32 v67, 0xffff0000, v141
	v_lshlrev_b32_e32 v68, 16, v142
	v_and_b32_e32 v69, 0xffff0000, v142
	v_lshlrev_b32_e32 v70, 16, v143
	v_and_b32_e32 v71, 0xffff0000, v143
	v_pk_fma_f32 v[80:81], v[40:41], v[8:9], v[72:73]
	v_pk_fma_f32 v[82:83], v[42:43], v[10:11], v[74:75]
	v_pk_fma_f32 v[84:85], v[44:45], v[12:13], v[76:77]
	v_pk_fma_f32 v[86:87], v[46:47], v[14:15], v[78:79]
	v_pk_fma_f32 v[80:81], v[48:49], v[16:17], v[80:81]
	v_pk_fma_f32 v[82:83], v[50:51], v[18:19], v[82:83]
	v_pk_fma_f32 v[84:85], v[52:53], v[20:21], v[84:85]
	v_pk_fma_f32 v[86:87], v[54:55], v[22:23], v[86:87]
	v_pk_fma_f32 v[80:81], v[56:57], v[24:25], v[80:81]
	v_pk_fma_f32 v[82:83], v[58:59], v[26:27], v[82:83]
	v_pk_fma_f32 v[84:85], v[60:61], v[28:29], v[84:85]
	v_pk_fma_f32 v[86:87], v[62:63], v[30:31], v[86:87]
	v_pk_fma_f32 v[80:81], v[64:65], v[32:33], v[80:81]
	v_pk_fma_f32 v[82:83], v[66:67], v[34:35], v[82:83]
	v_pk_fma_f32 v[84:85], v[68:69], v[36:37], v[84:85]
	v_pk_fma_f32 v[86:87], v[70:71], v[38:39], v[86:87]
	v_cvt_pk_bf16_f32 v88, v80, v81
	v_cvt_pk_bf16_f32 v89, v82, v83
	v_cvt_pk_bf16_f32 v90, v84, v85
	v_cvt_pk_bf16_f32 v91, v86, v87
	global_store_dwordx4 v1, v[88:91], s[10:11] offset:3072
	global_load_dwordx4 v[204:207], v1, s[8:9] offset:3072
	s_add_u32 s8, s8, 0x1000
	s_addc_u32 s9, s9, 0
	s_waitcnt vmcnt(23)
	v_lshlrev_b32_e32 v40, 16, v144
	v_and_b32_e32 v41, 0xffff0000, v144
	v_lshlrev_b32_e32 v42, 16, v145
	v_and_b32_e32 v43, 0xffff0000, v145
	v_lshlrev_b32_e32 v44, 16, v146
	v_and_b32_e32 v45, 0xffff0000, v146
	v_lshlrev_b32_e32 v46, 16, v147
	v_and_b32_e32 v47, 0xffff0000, v147
	v_pk_fma_f32 v[80:81], v[48:49], v[8:9], v[72:73]
	v_pk_fma_f32 v[82:83], v[50:51], v[10:11], v[74:75]
	v_pk_fma_f32 v[84:85], v[52:53], v[12:13], v[76:77]
	v_pk_fma_f32 v[86:87], v[54:55], v[14:15], v[78:79]
	v_pk_fma_f32 v[80:81], v[56:57], v[16:17], v[80:81]
	v_pk_fma_f32 v[82:83], v[58:59], v[18:19], v[82:83]
	v_pk_fma_f32 v[84:85], v[60:61], v[20:21], v[84:85]
	v_pk_fma_f32 v[86:87], v[62:63], v[22:23], v[86:87]
	v_pk_fma_f32 v[80:81], v[64:65], v[24:25], v[80:81]
	v_pk_fma_f32 v[82:83], v[66:67], v[26:27], v[82:83]
	v_pk_fma_f32 v[84:85], v[68:69], v[28:29], v[84:85]
	v_pk_fma_f32 v[86:87], v[70:71], v[30:31], v[86:87]
	v_pk_fma_f32 v[80:81], v[40:41], v[32:33], v[80:81]
	v_pk_fma_f32 v[82:83], v[42:43], v[34:35], v[82:83]
	v_pk_fma_f32 v[84:85], v[44:45], v[36:37], v[84:85]
	v_pk_fma_f32 v[86:87], v[46:47], v[38:39], v[86:87]
	v_cvt_pk_bf16_f32 v88, v80, v81
	v_cvt_pk_bf16_f32 v89, v82, v83
	v_cvt_pk_bf16_f32 v90, v84, v85
	v_cvt_pk_bf16_f32 v91, v86, v87
	s_add_u32 s10, s10, 0x1000
	s_addc_u32 s11, s11, 0
	global_store_dwordx4 v1, v[88:91], s[10:11]
	global_load_dwordx4 v[208:211], v1, s[8:9]
	s_waitcnt vmcnt(24)
	v_lshlrev_b32_e32 v48, 16, v148
	v_and_b32_e32 v49, 0xffff0000, v148
	v_lshlrev_b32_e32 v50, 16, v149
	v_and_b32_e32 v51, 0xffff0000, v149
	v_lshlrev_b32_e32 v52, 16, v150
	v_and_b32_e32 v53, 0xffff0000, v150
	v_lshlrev_b32_e32 v54, 16, v151
	v_and_b32_e32 v55, 0xffff0000, v151
	v_pk_fma_f32 v[80:81], v[56:57], v[8:9], v[72:73]
	v_pk_fma_f32 v[82:83], v[58:59], v[10:11], v[74:75]
	v_pk_fma_f32 v[84:85], v[60:61], v[12:13], v[76:77]
	v_pk_fma_f32 v[86:87], v[62:63], v[14:15], v[78:79]
	v_pk_fma_f32 v[80:81], v[64:65], v[16:17], v[80:81]
	v_pk_fma_f32 v[82:83], v[66:67], v[18:19], v[82:83]
	v_pk_fma_f32 v[84:85], v[68:69], v[20:21], v[84:85]
	v_pk_fma_f32 v[86:87], v[70:71], v[22:23], v[86:87]
	v_pk_fma_f32 v[80:81], v[40:41], v[24:25], v[80:81]
	v_pk_fma_f32 v[82:83], v[42:43], v[26:27], v[82:83]
	v_pk_fma_f32 v[84:85], v[44:45], v[28:29], v[84:85]
	v_pk_fma_f32 v[86:87], v[46:47], v[30:31], v[86:87]
	v_pk_fma_f32 v[80:81], v[48:49], v[32:33], v[80:81]
	v_pk_fma_f32 v[82:83], v[50:51], v[34:35], v[82:83]
	v_pk_fma_f32 v[84:85], v[52:53], v[36:37], v[84:85]
	v_pk_fma_f32 v[86:87], v[54:55], v[38:39], v[86:87]
	v_cvt_pk_bf16_f32 v88, v80, v81
	v_cvt_pk_bf16_f32 v89, v82, v83
	v_cvt_pk_bf16_f32 v90, v84, v85
	v_cvt_pk_bf16_f32 v91, v86, v87
	global_store_dwordx4 v1, v[88:91], s[10:11] offset:1024
	global_load_dwordx4 v[212:215], v1, s[8:9] offset:1024
	s_waitcnt vmcnt(25)
	v_lshlrev_b32_e32 v56, 16, v152
	v_and_b32_e32 v57, 0xffff0000, v152
	v_lshlrev_b32_e32 v58, 16, v153
	v_and_b32_e32 v59, 0xffff0000, v153
	v_lshlrev_b32_e32 v60, 16, v154
	v_and_b32_e32 v61, 0xffff0000, v154
	v_lshlrev_b32_e32 v62, 16, v155
	v_and_b32_e32 v63, 0xffff0000, v155
	v_pk_fma_f32 v[80:81], v[64:65], v[8:9], v[72:73]
	v_pk_fma_f32 v[82:83], v[66:67], v[10:11], v[74:75]
	v_pk_fma_f32 v[84:85], v[68:69], v[12:13], v[76:77]
	v_pk_fma_f32 v[86:87], v[70:71], v[14:15], v[78:79]
	v_pk_fma_f32 v[80:81], v[40:41], v[16:17], v[80:81]
	v_pk_fma_f32 v[82:83], v[42:43], v[18:19], v[82:83]
	v_pk_fma_f32 v[84:85], v[44:45], v[20:21], v[84:85]
	v_pk_fma_f32 v[86:87], v[46:47], v[22:23], v[86:87]
	v_pk_fma_f32 v[80:81], v[48:49], v[24:25], v[80:81]
	v_pk_fma_f32 v[82:83], v[50:51], v[26:27], v[82:83]
	v_pk_fma_f32 v[84:85], v[52:53], v[28:29], v[84:85]
	v_pk_fma_f32 v[86:87], v[54:55], v[30:31], v[86:87]
	v_pk_fma_f32 v[80:81], v[56:57], v[32:33], v[80:81]
	v_pk_fma_f32 v[82:83], v[58:59], v[34:35], v[82:83]
	v_pk_fma_f32 v[84:85], v[60:61], v[36:37], v[84:85]
	v_pk_fma_f32 v[86:87], v[62:63], v[38:39], v[86:87]
	v_cvt_pk_bf16_f32 v88, v80, v81
	v_cvt_pk_bf16_f32 v89, v82, v83
	v_cvt_pk_bf16_f32 v90, v84, v85
	v_cvt_pk_bf16_f32 v91, v86, v87
	global_store_dwordx4 v1, v[88:91], s[10:11] offset:2048
	global_load_dwordx4 v[216:219], v1, s[8:9] offset:2048
	s_waitcnt vmcnt(26)
	v_lshlrev_b32_e32 v64, 16, v156
	v_and_b32_e32 v65, 0xffff0000, v156
	v_lshlrev_b32_e32 v66, 16, v157
	v_and_b32_e32 v67, 0xffff0000, v157
	v_lshlrev_b32_e32 v68, 16, v158
	v_and_b32_e32 v69, 0xffff0000, v158
	v_lshlrev_b32_e32 v70, 16, v159
	v_and_b32_e32 v71, 0xffff0000, v159
	v_pk_fma_f32 v[80:81], v[40:41], v[8:9], v[72:73]
	v_pk_fma_f32 v[82:83], v[42:43], v[10:11], v[74:75]
	v_pk_fma_f32 v[84:85], v[44:45], v[12:13], v[76:77]
	v_pk_fma_f32 v[86:87], v[46:47], v[14:15], v[78:79]
	v_pk_fma_f32 v[80:81], v[48:49], v[16:17], v[80:81]
	v_pk_fma_f32 v[82:83], v[50:51], v[18:19], v[82:83]
	v_pk_fma_f32 v[84:85], v[52:53], v[20:21], v[84:85]
	v_pk_fma_f32 v[86:87], v[54:55], v[22:23], v[86:87]
	v_pk_fma_f32 v[80:81], v[56:57], v[24:25], v[80:81]
	v_pk_fma_f32 v[82:83], v[58:59], v[26:27], v[82:83]
	v_pk_fma_f32 v[84:85], v[60:61], v[28:29], v[84:85]
	v_pk_fma_f32 v[86:87], v[62:63], v[30:31], v[86:87]
	v_pk_fma_f32 v[80:81], v[64:65], v[32:33], v[80:81]
	v_pk_fma_f32 v[82:83], v[66:67], v[34:35], v[82:83]
	v_pk_fma_f32 v[84:85], v[68:69], v[36:37], v[84:85]
	v_pk_fma_f32 v[86:87], v[70:71], v[38:39], v[86:87]
	v_cvt_pk_bf16_f32 v88, v80, v81
	v_cvt_pk_bf16_f32 v89, v82, v83
	v_cvt_pk_bf16_f32 v90, v84, v85
	v_cvt_pk_bf16_f32 v91, v86, v87
	global_store_dwordx4 v1, v[88:91], s[10:11] offset:3072
	global_load_dwordx4 v[220:223], v1, s[8:9] offset:3072
	s_add_u32 s8, s8, 0x1000
	s_addc_u32 s9, s9, 0
	s_waitcnt vmcnt(27)
	v_lshlrev_b32_e32 v40, 16, v160
	v_and_b32_e32 v41, 0xffff0000, v160
	v_lshlrev_b32_e32 v42, 16, v161
	v_and_b32_e32 v43, 0xffff0000, v161
	v_lshlrev_b32_e32 v44, 16, v162
	v_and_b32_e32 v45, 0xffff0000, v162
	v_lshlrev_b32_e32 v46, 16, v163
	v_and_b32_e32 v47, 0xffff0000, v163
	v_pk_fma_f32 v[80:81], v[48:49], v[8:9], v[72:73]
	v_pk_fma_f32 v[82:83], v[50:51], v[10:11], v[74:75]
	v_pk_fma_f32 v[84:85], v[52:53], v[12:13], v[76:77]
	v_pk_fma_f32 v[86:87], v[54:55], v[14:15], v[78:79]
	v_pk_fma_f32 v[80:81], v[56:57], v[16:17], v[80:81]
	v_pk_fma_f32 v[82:83], v[58:59], v[18:19], v[82:83]
	v_pk_fma_f32 v[84:85], v[60:61], v[20:21], v[84:85]
	v_pk_fma_f32 v[86:87], v[62:63], v[22:23], v[86:87]
	v_pk_fma_f32 v[80:81], v[64:65], v[24:25], v[80:81]
	v_pk_fma_f32 v[82:83], v[66:67], v[26:27], v[82:83]
	v_pk_fma_f32 v[84:85], v[68:69], v[28:29], v[84:85]
	v_pk_fma_f32 v[86:87], v[70:71], v[30:31], v[86:87]
	v_pk_fma_f32 v[80:81], v[40:41], v[32:33], v[80:81]
	v_pk_fma_f32 v[82:83], v[42:43], v[34:35], v[82:83]
	v_pk_fma_f32 v[84:85], v[44:45], v[36:37], v[84:85]
	v_pk_fma_f32 v[86:87], v[46:47], v[38:39], v[86:87]
	v_cvt_pk_bf16_f32 v88, v80, v81
	v_cvt_pk_bf16_f32 v89, v82, v83
	v_cvt_pk_bf16_f32 v90, v84, v85
	v_cvt_pk_bf16_f32 v91, v86, v87
	s_add_u32 s10, s10, 0x1000
	s_addc_u32 s11, s11, 0
	global_store_dwordx4 v1, v[88:91], s[10:11]
	global_load_dwordx4 v[224:227], v1, s[8:9]
	s_waitcnt vmcnt(28)
	v_lshlrev_b32_e32 v48, 16, v164
	v_and_b32_e32 v49, 0xffff0000, v164
	v_lshlrev_b32_e32 v50, 16, v165
	v_and_b32_e32 v51, 0xffff0000, v165
	v_lshlrev_b32_e32 v52, 16, v166
	v_and_b32_e32 v53, 0xffff0000, v166
	v_lshlrev_b32_e32 v54, 16, v167
	v_and_b32_e32 v55, 0xffff0000, v167
	v_pk_fma_f32 v[80:81], v[56:57], v[8:9], v[72:73]
	v_pk_fma_f32 v[82:83], v[58:59], v[10:11], v[74:75]
	v_pk_fma_f32 v[84:85], v[60:61], v[12:13], v[76:77]
	v_pk_fma_f32 v[86:87], v[62:63], v[14:15], v[78:79]
	v_pk_fma_f32 v[80:81], v[64:65], v[16:17], v[80:81]
	v_pk_fma_f32 v[82:83], v[66:67], v[18:19], v[82:83]
	v_pk_fma_f32 v[84:85], v[68:69], v[20:21], v[84:85]
	v_pk_fma_f32 v[86:87], v[70:71], v[22:23], v[86:87]
	v_pk_fma_f32 v[80:81], v[40:41], v[24:25], v[80:81]
	v_pk_fma_f32 v[82:83], v[42:43], v[26:27], v[82:83]
	v_pk_fma_f32 v[84:85], v[44:45], v[28:29], v[84:85]
	v_pk_fma_f32 v[86:87], v[46:47], v[30:31], v[86:87]
	v_pk_fma_f32 v[80:81], v[48:49], v[32:33], v[80:81]
	v_pk_fma_f32 v[82:83], v[50:51], v[34:35], v[82:83]
	v_pk_fma_f32 v[84:85], v[52:53], v[36:37], v[84:85]
	v_pk_fma_f32 v[86:87], v[54:55], v[38:39], v[86:87]
	v_cvt_pk_bf16_f32 v88, v80, v81
	v_cvt_pk_bf16_f32 v89, v82, v83
	v_cvt_pk_bf16_f32 v90, v84, v85
	v_cvt_pk_bf16_f32 v91, v86, v87
	global_store_dwordx4 v1, v[88:91], s[10:11] offset:1024
	global_load_dwordx4 v[228:231], v1, s[8:9] offset:1024
	s_waitcnt vmcnt(29)
	v_lshlrev_b32_e32 v56, 16, v168
	v_and_b32_e32 v57, 0xffff0000, v168
	v_lshlrev_b32_e32 v58, 16, v169
	v_and_b32_e32 v59, 0xffff0000, v169
	v_lshlrev_b32_e32 v60, 16, v170
	v_and_b32_e32 v61, 0xffff0000, v170
	v_lshlrev_b32_e32 v62, 16, v171
	v_and_b32_e32 v63, 0xffff0000, v171
	v_pk_fma_f32 v[80:81], v[64:65], v[8:9], v[72:73]
	v_pk_fma_f32 v[82:83], v[66:67], v[10:11], v[74:75]
	v_pk_fma_f32 v[84:85], v[68:69], v[12:13], v[76:77]
	v_pk_fma_f32 v[86:87], v[70:71], v[14:15], v[78:79]
	v_pk_fma_f32 v[80:81], v[40:41], v[16:17], v[80:81]
	v_pk_fma_f32 v[82:83], v[42:43], v[18:19], v[82:83]
	v_pk_fma_f32 v[84:85], v[44:45], v[20:21], v[84:85]
	v_pk_fma_f32 v[86:87], v[46:47], v[22:23], v[86:87]
	v_pk_fma_f32 v[80:81], v[48:49], v[24:25], v[80:81]
	v_pk_fma_f32 v[82:83], v[50:51], v[26:27], v[82:83]
	v_pk_fma_f32 v[84:85], v[52:53], v[28:29], v[84:85]
	v_pk_fma_f32 v[86:87], v[54:55], v[30:31], v[86:87]
	v_pk_fma_f32 v[80:81], v[56:57], v[32:33], v[80:81]
	v_pk_fma_f32 v[82:83], v[58:59], v[34:35], v[82:83]
	v_pk_fma_f32 v[84:85], v[60:61], v[36:37], v[84:85]
	v_pk_fma_f32 v[86:87], v[62:63], v[38:39], v[86:87]
	v_cvt_pk_bf16_f32 v88, v80, v81
	v_cvt_pk_bf16_f32 v89, v82, v83
	v_cvt_pk_bf16_f32 v90, v84, v85
	v_cvt_pk_bf16_f32 v91, v86, v87
	global_store_dwordx4 v1, v[88:91], s[10:11] offset:2048
	global_load_dwordx4 v[232:235], v1, s[8:9] offset:2048
	s_waitcnt vmcnt(30)
	v_lshlrev_b32_e32 v64, 16, v172
	v_and_b32_e32 v65, 0xffff0000, v172
	v_lshlrev_b32_e32 v66, 16, v173
	v_and_b32_e32 v67, 0xffff0000, v173
	v_lshlrev_b32_e32 v68, 16, v174
	v_and_b32_e32 v69, 0xffff0000, v174
	v_lshlrev_b32_e32 v70, 16, v175
	v_and_b32_e32 v71, 0xffff0000, v175
	v_pk_fma_f32 v[80:81], v[40:41], v[8:9], v[72:73]
	v_pk_fma_f32 v[82:83], v[42:43], v[10:11], v[74:75]
	v_pk_fma_f32 v[84:85], v[44:45], v[12:13], v[76:77]
	v_pk_fma_f32 v[86:87], v[46:47], v[14:15], v[78:79]
	v_pk_fma_f32 v[80:81], v[48:49], v[16:17], v[80:81]
	v_pk_fma_f32 v[82:83], v[50:51], v[18:19], v[82:83]
	v_pk_fma_f32 v[84:85], v[52:53], v[20:21], v[84:85]
	v_pk_fma_f32 v[86:87], v[54:55], v[22:23], v[86:87]
	v_pk_fma_f32 v[80:81], v[56:57], v[24:25], v[80:81]
	v_pk_fma_f32 v[82:83], v[58:59], v[26:27], v[82:83]
	v_pk_fma_f32 v[84:85], v[60:61], v[28:29], v[84:85]
	v_pk_fma_f32 v[86:87], v[62:63], v[30:31], v[86:87]
	v_pk_fma_f32 v[80:81], v[64:65], v[32:33], v[80:81]
	v_pk_fma_f32 v[82:83], v[66:67], v[34:35], v[82:83]
	v_pk_fma_f32 v[84:85], v[68:69], v[36:37], v[84:85]
	v_pk_fma_f32 v[86:87], v[70:71], v[38:39], v[86:87]
	v_cvt_pk_bf16_f32 v88, v80, v81
	v_cvt_pk_bf16_f32 v89, v82, v83
	v_cvt_pk_bf16_f32 v90, v84, v85
	v_cvt_pk_bf16_f32 v91, v86, v87
	global_store_dwordx4 v1, v[88:91], s[10:11] offset:3072
	global_load_dwordx4 v[236:239], v1, s[8:9] offset:3072
	s_add_u32 s8, s8, 0x1000
	s_addc_u32 s9, s9, 0
	s_waitcnt vmcnt(30)
	v_lshlrev_b32_e32 v40, 16, v176
	v_and_b32_e32 v41, 0xffff0000, v176
	v_lshlrev_b32_e32 v42, 16, v177
	v_and_b32_e32 v43, 0xffff0000, v177
	v_lshlrev_b32_e32 v44, 16, v178
	v_and_b32_e32 v45, 0xffff0000, v178
	v_lshlrev_b32_e32 v46, 16, v179
	v_and_b32_e32 v47, 0xffff0000, v179
	v_pk_fma_f32 v[80:81], v[48:49], v[8:9], v[72:73]
	v_pk_fma_f32 v[82:83], v[50:51], v[10:11], v[74:75]
	v_pk_fma_f32 v[84:85], v[52:53], v[12:13], v[76:77]
	v_pk_fma_f32 v[86:87], v[54:55], v[14:15], v[78:79]
	v_pk_fma_f32 v[80:81], v[56:57], v[16:17], v[80:81]
	v_pk_fma_f32 v[82:83], v[58:59], v[18:19], v[82:83]
	v_pk_fma_f32 v[84:85], v[60:61], v[20:21], v[84:85]
	v_pk_fma_f32 v[86:87], v[62:63], v[22:23], v[86:87]
	v_pk_fma_f32 v[80:81], v[64:65], v[24:25], v[80:81]
	v_pk_fma_f32 v[82:83], v[66:67], v[26:27], v[82:83]
	v_pk_fma_f32 v[84:85], v[68:69], v[28:29], v[84:85]
	v_pk_fma_f32 v[86:87], v[70:71], v[30:31], v[86:87]
	v_pk_fma_f32 v[80:81], v[40:41], v[32:33], v[80:81]
	v_pk_fma_f32 v[82:83], v[42:43], v[34:35], v[82:83]
	v_pk_fma_f32 v[84:85], v[44:45], v[36:37], v[84:85]
	v_pk_fma_f32 v[86:87], v[46:47], v[38:39], v[86:87]
	v_cvt_pk_bf16_f32 v88, v80, v81
	v_cvt_pk_bf16_f32 v89, v82, v83
	v_cvt_pk_bf16_f32 v90, v84, v85
	v_cvt_pk_bf16_f32 v91, v86, v87
	s_add_u32 s10, s10, 0x1000
	s_addc_u32 s11, s11, 0
	global_store_dwordx4 v1, v[88:91], s[10:11]
	s_nop 1
	s_waitcnt vmcnt(29)
	v_lshlrev_b32_e32 v48, 16, v180
	v_and_b32_e32 v49, 0xffff0000, v180
	v_lshlrev_b32_e32 v50, 16, v181
	v_and_b32_e32 v51, 0xffff0000, v181
	v_lshlrev_b32_e32 v52, 16, v182
	v_and_b32_e32 v53, 0xffff0000, v182
	v_lshlrev_b32_e32 v54, 16, v183
	v_and_b32_e32 v55, 0xffff0000, v183
	v_pk_fma_f32 v[80:81], v[56:57], v[8:9], v[72:73]
	v_pk_fma_f32 v[82:83], v[58:59], v[10:11], v[74:75]
	v_pk_fma_f32 v[84:85], v[60:61], v[12:13], v[76:77]
	v_pk_fma_f32 v[86:87], v[62:63], v[14:15], v[78:79]
	v_pk_fma_f32 v[80:81], v[64:65], v[16:17], v[80:81]
	v_pk_fma_f32 v[82:83], v[66:67], v[18:19], v[82:83]
	v_pk_fma_f32 v[84:85], v[68:69], v[20:21], v[84:85]
	v_pk_fma_f32 v[86:87], v[70:71], v[22:23], v[86:87]
	v_pk_fma_f32 v[80:81], v[40:41], v[24:25], v[80:81]
	v_pk_fma_f32 v[82:83], v[42:43], v[26:27], v[82:83]
	v_pk_fma_f32 v[84:85], v[44:45], v[28:29], v[84:85]
	v_pk_fma_f32 v[86:87], v[46:47], v[30:31], v[86:87]
	v_pk_fma_f32 v[80:81], v[48:49], v[32:33], v[80:81]
	v_pk_fma_f32 v[82:83], v[50:51], v[34:35], v[82:83]
	v_pk_fma_f32 v[84:85], v[52:53], v[36:37], v[84:85]
	v_pk_fma_f32 v[86:87], v[54:55], v[38:39], v[86:87]
	v_cvt_pk_bf16_f32 v88, v80, v81
	v_cvt_pk_bf16_f32 v89, v82, v83
	v_cvt_pk_bf16_f32 v90, v84, v85
	v_cvt_pk_bf16_f32 v91, v86, v87
	global_store_dwordx4 v1, v[88:91], s[10:11] offset:1024
	s_nop 1
	s_waitcnt vmcnt(28)
	v_lshlrev_b32_e32 v56, 16, v184
	v_and_b32_e32 v57, 0xffff0000, v184
	v_lshlrev_b32_e32 v58, 16, v185
	v_and_b32_e32 v59, 0xffff0000, v185
	v_lshlrev_b32_e32 v60, 16, v186
	v_and_b32_e32 v61, 0xffff0000, v186
	v_lshlrev_b32_e32 v62, 16, v187
	v_and_b32_e32 v63, 0xffff0000, v187
	v_pk_fma_f32 v[80:81], v[64:65], v[8:9], v[72:73]
	v_pk_fma_f32 v[82:83], v[66:67], v[10:11], v[74:75]
	v_pk_fma_f32 v[84:85], v[68:69], v[12:13], v[76:77]
	v_pk_fma_f32 v[86:87], v[70:71], v[14:15], v[78:79]
	v_pk_fma_f32 v[80:81], v[40:41], v[16:17], v[80:81]
	v_pk_fma_f32 v[82:83], v[42:43], v[18:19], v[82:83]
	v_pk_fma_f32 v[84:85], v[44:45], v[20:21], v[84:85]
	v_pk_fma_f32 v[86:87], v[46:47], v[22:23], v[86:87]
	v_pk_fma_f32 v[80:81], v[48:49], v[24:25], v[80:81]
	v_pk_fma_f32 v[82:83], v[50:51], v[26:27], v[82:83]
	v_pk_fma_f32 v[84:85], v[52:53], v[28:29], v[84:85]
	v_pk_fma_f32 v[86:87], v[54:55], v[30:31], v[86:87]
	v_pk_fma_f32 v[80:81], v[56:57], v[32:33], v[80:81]
	v_pk_fma_f32 v[82:83], v[58:59], v[34:35], v[82:83]
	v_pk_fma_f32 v[84:85], v[60:61], v[36:37], v[84:85]
	v_pk_fma_f32 v[86:87], v[62:63], v[38:39], v[86:87]
	v_cvt_pk_bf16_f32 v88, v80, v81
	v_cvt_pk_bf16_f32 v89, v82, v83
	v_cvt_pk_bf16_f32 v90, v84, v85
	v_cvt_pk_bf16_f32 v91, v86, v87
	global_store_dwordx4 v1, v[88:91], s[10:11] offset:2048
	s_nop 1
	s_waitcnt vmcnt(27)
	v_lshlrev_b32_e32 v64, 16, v188
	v_and_b32_e32 v65, 0xffff0000, v188
	v_lshlrev_b32_e32 v66, 16, v189
	v_and_b32_e32 v67, 0xffff0000, v189
	v_lshlrev_b32_e32 v68, 16, v190
	v_and_b32_e32 v69, 0xffff0000, v190
	v_lshlrev_b32_e32 v70, 16, v191
	v_and_b32_e32 v71, 0xffff0000, v191
	v_pk_fma_f32 v[80:81], v[40:41], v[8:9], v[72:73]
	v_pk_fma_f32 v[82:83], v[42:43], v[10:11], v[74:75]
	v_pk_fma_f32 v[84:85], v[44:45], v[12:13], v[76:77]
	v_pk_fma_f32 v[86:87], v[46:47], v[14:15], v[78:79]
	v_pk_fma_f32 v[80:81], v[48:49], v[16:17], v[80:81]
	v_pk_fma_f32 v[82:83], v[50:51], v[18:19], v[82:83]
	v_pk_fma_f32 v[84:85], v[52:53], v[20:21], v[84:85]
	v_pk_fma_f32 v[86:87], v[54:55], v[22:23], v[86:87]
	v_pk_fma_f32 v[80:81], v[56:57], v[24:25], v[80:81]
	v_pk_fma_f32 v[82:83], v[58:59], v[26:27], v[82:83]
	v_pk_fma_f32 v[84:85], v[60:61], v[28:29], v[84:85]
	v_pk_fma_f32 v[86:87], v[62:63], v[30:31], v[86:87]
	v_pk_fma_f32 v[80:81], v[64:65], v[32:33], v[80:81]
	v_pk_fma_f32 v[82:83], v[66:67], v[34:35], v[82:83]
	v_pk_fma_f32 v[84:85], v[68:69], v[36:37], v[84:85]
	v_pk_fma_f32 v[86:87], v[70:71], v[38:39], v[86:87]
	v_cvt_pk_bf16_f32 v88, v80, v81
	v_cvt_pk_bf16_f32 v89, v82, v83
	v_cvt_pk_bf16_f32 v90, v84, v85
	v_cvt_pk_bf16_f32 v91, v86, v87
	global_store_dwordx4 v1, v[88:91], s[10:11] offset:3072
	s_nop 1
	s_waitcnt vmcnt(26)
	v_lshlrev_b32_e32 v40, 16, v192
	v_and_b32_e32 v41, 0xffff0000, v192
	v_lshlrev_b32_e32 v42, 16, v193
	v_and_b32_e32 v43, 0xffff0000, v193
	v_lshlrev_b32_e32 v44, 16, v194
	v_and_b32_e32 v45, 0xffff0000, v194
	v_lshlrev_b32_e32 v46, 16, v195
	v_and_b32_e32 v47, 0xffff0000, v195
	v_pk_fma_f32 v[80:81], v[48:49], v[8:9], v[72:73]
	v_pk_fma_f32 v[82:83], v[50:51], v[10:11], v[74:75]
	v_pk_fma_f32 v[84:85], v[52:53], v[12:13], v[76:77]
	v_pk_fma_f32 v[86:87], v[54:55], v[14:15], v[78:79]
	v_pk_fma_f32 v[80:81], v[56:57], v[16:17], v[80:81]
	v_pk_fma_f32 v[82:83], v[58:59], v[18:19], v[82:83]
	v_pk_fma_f32 v[84:85], v[60:61], v[20:21], v[84:85]
	v_pk_fma_f32 v[86:87], v[62:63], v[22:23], v[86:87]
	v_pk_fma_f32 v[80:81], v[64:65], v[24:25], v[80:81]
	v_pk_fma_f32 v[82:83], v[66:67], v[26:27], v[82:83]
	v_pk_fma_f32 v[84:85], v[68:69], v[28:29], v[84:85]
	v_pk_fma_f32 v[86:87], v[70:71], v[30:31], v[86:87]
	v_pk_fma_f32 v[80:81], v[40:41], v[32:33], v[80:81]
	v_pk_fma_f32 v[82:83], v[42:43], v[34:35], v[82:83]
	v_pk_fma_f32 v[84:85], v[44:45], v[36:37], v[84:85]
	v_pk_fma_f32 v[86:87], v[46:47], v[38:39], v[86:87]
	v_cvt_pk_bf16_f32 v88, v80, v81
	v_cvt_pk_bf16_f32 v89, v82, v83
	v_cvt_pk_bf16_f32 v90, v84, v85
	v_cvt_pk_bf16_f32 v91, v86, v87
	s_add_u32 s10, s10, 0x1000
	s_addc_u32 s11, s11, 0
	global_store_dwordx4 v1, v[88:91], s[10:11]
	s_nop 1
	s_waitcnt vmcnt(25)
	v_lshlrev_b32_e32 v48, 16, v196
	v_and_b32_e32 v49, 0xffff0000, v196
	v_lshlrev_b32_e32 v50, 16, v197
	v_and_b32_e32 v51, 0xffff0000, v197
	v_lshlrev_b32_e32 v52, 16, v198
	v_and_b32_e32 v53, 0xffff0000, v198
	v_lshlrev_b32_e32 v54, 16, v199
	v_and_b32_e32 v55, 0xffff0000, v199
	v_pk_fma_f32 v[80:81], v[56:57], v[8:9], v[72:73]
	v_pk_fma_f32 v[82:83], v[58:59], v[10:11], v[74:75]
	v_pk_fma_f32 v[84:85], v[60:61], v[12:13], v[76:77]
	v_pk_fma_f32 v[86:87], v[62:63], v[14:15], v[78:79]
	v_pk_fma_f32 v[80:81], v[64:65], v[16:17], v[80:81]
	v_pk_fma_f32 v[82:83], v[66:67], v[18:19], v[82:83]
	v_pk_fma_f32 v[84:85], v[68:69], v[20:21], v[84:85]
	v_pk_fma_f32 v[86:87], v[70:71], v[22:23], v[86:87]
	v_pk_fma_f32 v[80:81], v[40:41], v[24:25], v[80:81]
	v_pk_fma_f32 v[82:83], v[42:43], v[26:27], v[82:83]
	v_pk_fma_f32 v[84:85], v[44:45], v[28:29], v[84:85]
	v_pk_fma_f32 v[86:87], v[46:47], v[30:31], v[86:87]
	v_pk_fma_f32 v[80:81], v[48:49], v[32:33], v[80:81]
	v_pk_fma_f32 v[82:83], v[50:51], v[34:35], v[82:83]
	v_pk_fma_f32 v[84:85], v[52:53], v[36:37], v[84:85]
	v_pk_fma_f32 v[86:87], v[54:55], v[38:39], v[86:87]
	v_cvt_pk_bf16_f32 v88, v80, v81
	v_cvt_pk_bf16_f32 v89, v82, v83
	v_cvt_pk_bf16_f32 v90, v84, v85
	v_cvt_pk_bf16_f32 v91, v86, v87
	global_store_dwordx4 v1, v[88:91], s[10:11] offset:1024
	s_nop 1
	s_waitcnt vmcnt(24)
	v_lshlrev_b32_e32 v56, 16, v200
	v_and_b32_e32 v57, 0xffff0000, v200
	v_lshlrev_b32_e32 v58, 16, v201
	v_and_b32_e32 v59, 0xffff0000, v201
	v_lshlrev_b32_e32 v60, 16, v202
	v_and_b32_e32 v61, 0xffff0000, v202
	v_lshlrev_b32_e32 v62, 16, v203
	v_and_b32_e32 v63, 0xffff0000, v203
	v_pk_fma_f32 v[80:81], v[64:65], v[8:9], v[72:73]
	v_pk_fma_f32 v[82:83], v[66:67], v[10:11], v[74:75]
	v_pk_fma_f32 v[84:85], v[68:69], v[12:13], v[76:77]
	v_pk_fma_f32 v[86:87], v[70:71], v[14:15], v[78:79]
	v_pk_fma_f32 v[80:81], v[40:41], v[16:17], v[80:81]
	v_pk_fma_f32 v[82:83], v[42:43], v[18:19], v[82:83]
	v_pk_fma_f32 v[84:85], v[44:45], v[20:21], v[84:85]
	v_pk_fma_f32 v[86:87], v[46:47], v[22:23], v[86:87]
	v_pk_fma_f32 v[80:81], v[48:49], v[24:25], v[80:81]
	v_pk_fma_f32 v[82:83], v[50:51], v[26:27], v[82:83]
	v_pk_fma_f32 v[84:85], v[52:53], v[28:29], v[84:85]
	v_pk_fma_f32 v[86:87], v[54:55], v[30:31], v[86:87]
	v_pk_fma_f32 v[80:81], v[56:57], v[32:33], v[80:81]
	v_pk_fma_f32 v[82:83], v[58:59], v[34:35], v[82:83]
	v_pk_fma_f32 v[84:85], v[60:61], v[36:37], v[84:85]
	v_pk_fma_f32 v[86:87], v[62:63], v[38:39], v[86:87]
	v_cvt_pk_bf16_f32 v88, v80, v81
	v_cvt_pk_bf16_f32 v89, v82, v83
	v_cvt_pk_bf16_f32 v90, v84, v85
	v_cvt_pk_bf16_f32 v91, v86, v87
	global_store_dwordx4 v1, v[88:91], s[10:11] offset:2048
	s_nop 1
	s_waitcnt vmcnt(23)
	v_lshlrev_b32_e32 v64, 16, v204
	v_and_b32_e32 v65, 0xffff0000, v204
	v_lshlrev_b32_e32 v66, 16, v205
	v_and_b32_e32 v67, 0xffff0000, v205
	v_lshlrev_b32_e32 v68, 16, v206
	v_and_b32_e32 v69, 0xffff0000, v206
	v_lshlrev_b32_e32 v70, 16, v207
	v_and_b32_e32 v71, 0xffff0000, v207
	v_pk_fma_f32 v[80:81], v[40:41], v[8:9], v[72:73]
	v_pk_fma_f32 v[82:83], v[42:43], v[10:11], v[74:75]
	v_pk_fma_f32 v[84:85], v[44:45], v[12:13], v[76:77]
	v_pk_fma_f32 v[86:87], v[46:47], v[14:15], v[78:79]
	v_pk_fma_f32 v[80:81], v[48:49], v[16:17], v[80:81]
	v_pk_fma_f32 v[82:83], v[50:51], v[18:19], v[82:83]
	v_pk_fma_f32 v[84:85], v[52:53], v[20:21], v[84:85]
	v_pk_fma_f32 v[86:87], v[54:55], v[22:23], v[86:87]
	v_pk_fma_f32 v[80:81], v[56:57], v[24:25], v[80:81]
	v_pk_fma_f32 v[82:83], v[58:59], v[26:27], v[82:83]
	v_pk_fma_f32 v[84:85], v[60:61], v[28:29], v[84:85]
	v_pk_fma_f32 v[86:87], v[62:63], v[30:31], v[86:87]
	v_pk_fma_f32 v[80:81], v[64:65], v[32:33], v[80:81]
	v_pk_fma_f32 v[82:83], v[66:67], v[34:35], v[82:83]
	v_pk_fma_f32 v[84:85], v[68:69], v[36:37], v[84:85]
	v_pk_fma_f32 v[86:87], v[70:71], v[38:39], v[86:87]
	v_cvt_pk_bf16_f32 v88, v80, v81
	v_cvt_pk_bf16_f32 v89, v82, v83
	v_cvt_pk_bf16_f32 v90, v84, v85
	v_cvt_pk_bf16_f32 v91, v86, v87
	global_store_dwordx4 v1, v[88:91], s[10:11] offset:3072
	s_nop 1
	s_waitcnt vmcnt(22)
	v_lshlrev_b32_e32 v40, 16, v208
	v_and_b32_e32 v41, 0xffff0000, v208
	v_lshlrev_b32_e32 v42, 16, v209
	v_and_b32_e32 v43, 0xffff0000, v209
	v_lshlrev_b32_e32 v44, 16, v210
	v_and_b32_e32 v45, 0xffff0000, v210
	v_lshlrev_b32_e32 v46, 16, v211
	v_and_b32_e32 v47, 0xffff0000, v211
	v_pk_fma_f32 v[80:81], v[48:49], v[8:9], v[72:73]
	v_pk_fma_f32 v[82:83], v[50:51], v[10:11], v[74:75]
	v_pk_fma_f32 v[84:85], v[52:53], v[12:13], v[76:77]
	v_pk_fma_f32 v[86:87], v[54:55], v[14:15], v[78:79]
	v_pk_fma_f32 v[80:81], v[56:57], v[16:17], v[80:81]
	v_pk_fma_f32 v[82:83], v[58:59], v[18:19], v[82:83]
	v_pk_fma_f32 v[84:85], v[60:61], v[20:21], v[84:85]
	v_pk_fma_f32 v[86:87], v[62:63], v[22:23], v[86:87]
	v_pk_fma_f32 v[80:81], v[64:65], v[24:25], v[80:81]
	v_pk_fma_f32 v[82:83], v[66:67], v[26:27], v[82:83]
	v_pk_fma_f32 v[84:85], v[68:69], v[28:29], v[84:85]
	v_pk_fma_f32 v[86:87], v[70:71], v[30:31], v[86:87]
	v_pk_fma_f32 v[80:81], v[40:41], v[32:33], v[80:81]
	v_pk_fma_f32 v[82:83], v[42:43], v[34:35], v[82:83]
	v_pk_fma_f32 v[84:85], v[44:45], v[36:37], v[84:85]
	v_pk_fma_f32 v[86:87], v[46:47], v[38:39], v[86:87]
	v_cvt_pk_bf16_f32 v88, v80, v81
	v_cvt_pk_bf16_f32 v89, v82, v83
	v_cvt_pk_bf16_f32 v90, v84, v85
	v_cvt_pk_bf16_f32 v91, v86, v87
	s_add_u32 s10, s10, 0x1000
	s_addc_u32 s11, s11, 0
	global_store_dwordx4 v1, v[88:91], s[10:11]
	s_nop 1
	s_waitcnt vmcnt(21)
	v_lshlrev_b32_e32 v48, 16, v212
	v_and_b32_e32 v49, 0xffff0000, v212
	v_lshlrev_b32_e32 v50, 16, v213
	v_and_b32_e32 v51, 0xffff0000, v213
	v_lshlrev_b32_e32 v52, 16, v214
	v_and_b32_e32 v53, 0xffff0000, v214
	v_lshlrev_b32_e32 v54, 16, v215
	v_and_b32_e32 v55, 0xffff0000, v215
	v_pk_fma_f32 v[80:81], v[56:57], v[8:9], v[72:73]
	v_pk_fma_f32 v[82:83], v[58:59], v[10:11], v[74:75]
	v_pk_fma_f32 v[84:85], v[60:61], v[12:13], v[76:77]
	v_pk_fma_f32 v[86:87], v[62:63], v[14:15], v[78:79]
	v_pk_fma_f32 v[80:81], v[64:65], v[16:17], v[80:81]
	v_pk_fma_f32 v[82:83], v[66:67], v[18:19], v[82:83]
	v_pk_fma_f32 v[84:85], v[68:69], v[20:21], v[84:85]
	v_pk_fma_f32 v[86:87], v[70:71], v[22:23], v[86:87]
	v_pk_fma_f32 v[80:81], v[40:41], v[24:25], v[80:81]
	v_pk_fma_f32 v[82:83], v[42:43], v[26:27], v[82:83]
	v_pk_fma_f32 v[84:85], v[44:45], v[28:29], v[84:85]
	v_pk_fma_f32 v[86:87], v[46:47], v[30:31], v[86:87]
	v_pk_fma_f32 v[80:81], v[48:49], v[32:33], v[80:81]
	v_pk_fma_f32 v[82:83], v[50:51], v[34:35], v[82:83]
	v_pk_fma_f32 v[84:85], v[52:53], v[36:37], v[84:85]
	v_pk_fma_f32 v[86:87], v[54:55], v[38:39], v[86:87]
	v_cvt_pk_bf16_f32 v88, v80, v81
	v_cvt_pk_bf16_f32 v89, v82, v83
	v_cvt_pk_bf16_f32 v90, v84, v85
	v_cvt_pk_bf16_f32 v91, v86, v87
	global_store_dwordx4 v1, v[88:91], s[10:11] offset:1024
	s_nop 1
	s_waitcnt vmcnt(20)
	v_lshlrev_b32_e32 v56, 16, v216
	v_and_b32_e32 v57, 0xffff0000, v216
	v_lshlrev_b32_e32 v58, 16, v217
	v_and_b32_e32 v59, 0xffff0000, v217
	v_lshlrev_b32_e32 v60, 16, v218
	v_and_b32_e32 v61, 0xffff0000, v218
	v_lshlrev_b32_e32 v62, 16, v219
	v_and_b32_e32 v63, 0xffff0000, v219
	v_pk_fma_f32 v[80:81], v[64:65], v[8:9], v[72:73]
	v_pk_fma_f32 v[82:83], v[66:67], v[10:11], v[74:75]
	v_pk_fma_f32 v[84:85], v[68:69], v[12:13], v[76:77]
	v_pk_fma_f32 v[86:87], v[70:71], v[14:15], v[78:79]
	v_pk_fma_f32 v[80:81], v[40:41], v[16:17], v[80:81]
	v_pk_fma_f32 v[82:83], v[42:43], v[18:19], v[82:83]
	v_pk_fma_f32 v[84:85], v[44:45], v[20:21], v[84:85]
	v_pk_fma_f32 v[86:87], v[46:47], v[22:23], v[86:87]
	v_pk_fma_f32 v[80:81], v[48:49], v[24:25], v[80:81]
	v_pk_fma_f32 v[82:83], v[50:51], v[26:27], v[82:83]
	v_pk_fma_f32 v[84:85], v[52:53], v[28:29], v[84:85]
	v_pk_fma_f32 v[86:87], v[54:55], v[30:31], v[86:87]
	v_pk_fma_f32 v[80:81], v[56:57], v[32:33], v[80:81]
	v_pk_fma_f32 v[82:83], v[58:59], v[34:35], v[82:83]
	v_pk_fma_f32 v[84:85], v[60:61], v[36:37], v[84:85]
	v_pk_fma_f32 v[86:87], v[62:63], v[38:39], v[86:87]
	v_cvt_pk_bf16_f32 v88, v80, v81
	v_cvt_pk_bf16_f32 v89, v82, v83
	v_cvt_pk_bf16_f32 v90, v84, v85
	v_cvt_pk_bf16_f32 v91, v86, v87
	global_store_dwordx4 v1, v[88:91], s[10:11] offset:2048
	s_nop 1
	s_waitcnt vmcnt(19)
	v_lshlrev_b32_e32 v64, 16, v220
	v_and_b32_e32 v65, 0xffff0000, v220
	v_lshlrev_b32_e32 v66, 16, v221
	v_and_b32_e32 v67, 0xffff0000, v221
	v_lshlrev_b32_e32 v68, 16, v222
	v_and_b32_e32 v69, 0xffff0000, v222
	v_lshlrev_b32_e32 v70, 16, v223
	v_and_b32_e32 v71, 0xffff0000, v223
	v_pk_fma_f32 v[80:81], v[40:41], v[8:9], v[72:73]
	v_pk_fma_f32 v[82:83], v[42:43], v[10:11], v[74:75]
	v_pk_fma_f32 v[84:85], v[44:45], v[12:13], v[76:77]
	v_pk_fma_f32 v[86:87], v[46:47], v[14:15], v[78:79]
	v_pk_fma_f32 v[80:81], v[48:49], v[16:17], v[80:81]
	v_pk_fma_f32 v[82:83], v[50:51], v[18:19], v[82:83]
	v_pk_fma_f32 v[84:85], v[52:53], v[20:21], v[84:85]
	v_pk_fma_f32 v[86:87], v[54:55], v[22:23], v[86:87]
	v_pk_fma_f32 v[80:81], v[56:57], v[24:25], v[80:81]
	v_pk_fma_f32 v[82:83], v[58:59], v[26:27], v[82:83]
	v_pk_fma_f32 v[84:85], v[60:61], v[28:29], v[84:85]
	v_pk_fma_f32 v[86:87], v[62:63], v[30:31], v[86:87]
	v_pk_fma_f32 v[80:81], v[64:65], v[32:33], v[80:81]
	v_pk_fma_f32 v[82:83], v[66:67], v[34:35], v[82:83]
	v_pk_fma_f32 v[84:85], v[68:69], v[36:37], v[84:85]
	v_pk_fma_f32 v[86:87], v[70:71], v[38:39], v[86:87]
	v_cvt_pk_bf16_f32 v88, v80, v81
	v_cvt_pk_bf16_f32 v89, v82, v83
	v_cvt_pk_bf16_f32 v90, v84, v85
	v_cvt_pk_bf16_f32 v91, v86, v87
	global_store_dwordx4 v1, v[88:91], s[10:11] offset:3072
	s_nop 1
	s_waitcnt vmcnt(18)
	v_lshlrev_b32_e32 v40, 16, v224
	v_and_b32_e32 v41, 0xffff0000, v224
	v_lshlrev_b32_e32 v42, 16, v225
	v_and_b32_e32 v43, 0xffff0000, v225
	v_lshlrev_b32_e32 v44, 16, v226
	v_and_b32_e32 v45, 0xffff0000, v226
	v_lshlrev_b32_e32 v46, 16, v227
	v_and_b32_e32 v47, 0xffff0000, v227
	v_pk_fma_f32 v[80:81], v[48:49], v[8:9], v[72:73]
	v_pk_fma_f32 v[82:83], v[50:51], v[10:11], v[74:75]
	v_pk_fma_f32 v[84:85], v[52:53], v[12:13], v[76:77]
	v_pk_fma_f32 v[86:87], v[54:55], v[14:15], v[78:79]
	v_pk_fma_f32 v[80:81], v[56:57], v[16:17], v[80:81]
	v_pk_fma_f32 v[82:83], v[58:59], v[18:19], v[82:83]
	v_pk_fma_f32 v[84:85], v[60:61], v[20:21], v[84:85]
	v_pk_fma_f32 v[86:87], v[62:63], v[22:23], v[86:87]
	v_pk_fma_f32 v[80:81], v[64:65], v[24:25], v[80:81]
	v_pk_fma_f32 v[82:83], v[66:67], v[26:27], v[82:83]
	v_pk_fma_f32 v[84:85], v[68:69], v[28:29], v[84:85]
	v_pk_fma_f32 v[86:87], v[70:71], v[30:31], v[86:87]
	v_pk_fma_f32 v[80:81], v[40:41], v[32:33], v[80:81]
	v_pk_fma_f32 v[82:83], v[42:43], v[34:35], v[82:83]
	v_pk_fma_f32 v[84:85], v[44:45], v[36:37], v[84:85]
	v_pk_fma_f32 v[86:87], v[46:47], v[38:39], v[86:87]
	v_cvt_pk_bf16_f32 v88, v80, v81
	v_cvt_pk_bf16_f32 v89, v82, v83
	v_cvt_pk_bf16_f32 v90, v84, v85
	v_cvt_pk_bf16_f32 v91, v86, v87
	s_add_u32 s10, s10, 0x1000
	s_addc_u32 s11, s11, 0
	global_store_dwordx4 v1, v[88:91], s[10:11]
	s_nop 1
	s_waitcnt vmcnt(17)
	v_lshlrev_b32_e32 v48, 16, v228
	v_and_b32_e32 v49, 0xffff0000, v228
	v_lshlrev_b32_e32 v50, 16, v229
	v_and_b32_e32 v51, 0xffff0000, v229
	v_lshlrev_b32_e32 v52, 16, v230
	v_and_b32_e32 v53, 0xffff0000, v230
	v_lshlrev_b32_e32 v54, 16, v231
	v_and_b32_e32 v55, 0xffff0000, v231
	v_pk_fma_f32 v[80:81], v[56:57], v[8:9], v[72:73]
	v_pk_fma_f32 v[82:83], v[58:59], v[10:11], v[74:75]
	v_pk_fma_f32 v[84:85], v[60:61], v[12:13], v[76:77]
	v_pk_fma_f32 v[86:87], v[62:63], v[14:15], v[78:79]
	v_pk_fma_f32 v[80:81], v[64:65], v[16:17], v[80:81]
	v_pk_fma_f32 v[82:83], v[66:67], v[18:19], v[82:83]
	v_pk_fma_f32 v[84:85], v[68:69], v[20:21], v[84:85]
	v_pk_fma_f32 v[86:87], v[70:71], v[22:23], v[86:87]
	v_pk_fma_f32 v[80:81], v[40:41], v[24:25], v[80:81]
	v_pk_fma_f32 v[82:83], v[42:43], v[26:27], v[82:83]
	v_pk_fma_f32 v[84:85], v[44:45], v[28:29], v[84:85]
	v_pk_fma_f32 v[86:87], v[46:47], v[30:31], v[86:87]
	v_pk_fma_f32 v[80:81], v[48:49], v[32:33], v[80:81]
	v_pk_fma_f32 v[82:83], v[50:51], v[34:35], v[82:83]
	v_pk_fma_f32 v[84:85], v[52:53], v[36:37], v[84:85]
	v_pk_fma_f32 v[86:87], v[54:55], v[38:39], v[86:87]
	v_cvt_pk_bf16_f32 v88, v80, v81
	v_cvt_pk_bf16_f32 v89, v82, v83
	v_cvt_pk_bf16_f32 v90, v84, v85
	v_cvt_pk_bf16_f32 v91, v86, v87
	global_store_dwordx4 v1, v[88:91], s[10:11] offset:1024
	s_nop 1
	s_waitcnt vmcnt(16)
	v_lshlrev_b32_e32 v56, 16, v232
	v_and_b32_e32 v57, 0xffff0000, v232
	v_lshlrev_b32_e32 v58, 16, v233
	v_and_b32_e32 v59, 0xffff0000, v233
	v_lshlrev_b32_e32 v60, 16, v234
	v_and_b32_e32 v61, 0xffff0000, v234
	v_lshlrev_b32_e32 v62, 16, v235
	v_and_b32_e32 v63, 0xffff0000, v235
	v_pk_fma_f32 v[80:81], v[64:65], v[8:9], v[72:73]
	v_pk_fma_f32 v[82:83], v[66:67], v[10:11], v[74:75]
	v_pk_fma_f32 v[84:85], v[68:69], v[12:13], v[76:77]
	v_pk_fma_f32 v[86:87], v[70:71], v[14:15], v[78:79]
	v_pk_fma_f32 v[80:81], v[40:41], v[16:17], v[80:81]
	v_pk_fma_f32 v[82:83], v[42:43], v[18:19], v[82:83]
	v_pk_fma_f32 v[84:85], v[44:45], v[20:21], v[84:85]
	v_pk_fma_f32 v[86:87], v[46:47], v[22:23], v[86:87]
	v_pk_fma_f32 v[80:81], v[48:49], v[24:25], v[80:81]
	v_pk_fma_f32 v[82:83], v[50:51], v[26:27], v[82:83]
	v_pk_fma_f32 v[84:85], v[52:53], v[28:29], v[84:85]
	v_pk_fma_f32 v[86:87], v[54:55], v[30:31], v[86:87]
	v_pk_fma_f32 v[80:81], v[56:57], v[32:33], v[80:81]
	v_pk_fma_f32 v[82:83], v[58:59], v[34:35], v[82:83]
	v_pk_fma_f32 v[84:85], v[60:61], v[36:37], v[84:85]
	v_pk_fma_f32 v[86:87], v[62:63], v[38:39], v[86:87]
	v_cvt_pk_bf16_f32 v88, v80, v81
	v_cvt_pk_bf16_f32 v89, v82, v83
	v_cvt_pk_bf16_f32 v90, v84, v85
	v_cvt_pk_bf16_f32 v91, v86, v87
	global_store_dwordx4 v1, v[88:91], s[10:11] offset:2048
	s_nop 1
	s_waitcnt vmcnt(15)
	v_lshlrev_b32_e32 v64, 16, v236
	v_and_b32_e32 v65, 0xffff0000, v236
	v_lshlrev_b32_e32 v66, 16, v237
	v_and_b32_e32 v67, 0xffff0000, v237
	v_lshlrev_b32_e32 v68, 16, v238
	v_and_b32_e32 v69, 0xffff0000, v238
	v_lshlrev_b32_e32 v70, 16, v239
	v_and_b32_e32 v71, 0xffff0000, v239
	v_pk_fma_f32 v[80:81], v[40:41], v[8:9], v[72:73]
	v_pk_fma_f32 v[82:83], v[42:43], v[10:11], v[74:75]
	v_pk_fma_f32 v[84:85], v[44:45], v[12:13], v[76:77]
	v_pk_fma_f32 v[86:87], v[46:47], v[14:15], v[78:79]
	v_pk_fma_f32 v[80:81], v[48:49], v[16:17], v[80:81]
	v_pk_fma_f32 v[82:83], v[50:51], v[18:19], v[82:83]
	v_pk_fma_f32 v[84:85], v[52:53], v[20:21], v[84:85]
	v_pk_fma_f32 v[86:87], v[54:55], v[22:23], v[86:87]
	v_pk_fma_f32 v[80:81], v[56:57], v[24:25], v[80:81]
	v_pk_fma_f32 v[82:83], v[58:59], v[26:27], v[82:83]
	v_pk_fma_f32 v[84:85], v[60:61], v[28:29], v[84:85]
	v_pk_fma_f32 v[86:87], v[62:63], v[30:31], v[86:87]
	v_pk_fma_f32 v[80:81], v[64:65], v[32:33], v[80:81]
	v_pk_fma_f32 v[82:83], v[66:67], v[34:35], v[82:83]
	v_pk_fma_f32 v[84:85], v[68:69], v[36:37], v[84:85]
	v_pk_fma_f32 v[86:87], v[70:71], v[38:39], v[86:87]
	v_cvt_pk_bf16_f32 v88, v80, v81
	v_cvt_pk_bf16_f32 v89, v82, v83
	v_cvt_pk_bf16_f32 v90, v84, v85
	v_cvt_pk_bf16_f32 v91, v86, v87
	global_store_dwordx4 v1, v[88:91], s[10:11] offset:3072
	s_nop 1
	s_branch .Lp2b_done
